# hand-written attention loop heads aligned to 64 bytes (code placement no longer depends on upstream edits)
# speedup vs baseline: 1.0079x; 1.0076x over previous
.Lfar_p1:
	v_add_u32_e32 v175, s27, v198
	ds_read_b128 v[178:181], v175
	ds_read_b128 v[206:209], v175 offset:32
	ds_read_b128 v[210:213], v175 offset:64
	ds_read_b128 v[214:217], v175 offset:96
	ds_read_b128 v[230:233], v175 offset:4608
	ds_read_b128 v[236:239], v175 offset:4640
	s_cmp_gt_i32 s30, -1
	s_cselect_b64 vcc, -1, 0
	s_nop 1
	v_cndmask_b32_e32 v80, v204, v205, vcc
	v_mov_b32_e32 v81, v80
	v_mov_b32_e32 v82, v80
	v_mov_b32_e32 v83, v80
	v_mov_b32_e32 v84, v80
	v_mov_b32_e32 v85, v80
	v_mov_b32_e32 v86, v80
	v_mov_b32_e32 v87, v80
	v_mov_b32_e32 v88, v80
	v_mov_b32_e32 v89, v80
	v_mov_b32_e32 v90, v80
	v_mov_b32_e32 v91, v80
	v_mov_b32_e32 v92, v80
	v_mov_b32_e32 v93, v80
	v_mov_b32_e32 v94, v80
	v_mov_b32_e32 v95, v80
	s_nop 0
	.p2align 6

.Lfar_p2:
	v_add_u32_e32 v169, s13, v198
	ds_read_b128 v[178:181], v169
	ds_read_b128 v[206:209], v169 offset:32
	ds_read_b128 v[210:213], v169 offset:64
	ds_read_b128 v[214:217], v169 offset:96
	ds_read_b128 v[230:233], v169 offset:4608
	ds_read_b128 v[236:239], v169 offset:4640
	s_cmp_gt_i32 s24, -1
	s_cselect_b64 vcc, -1, 0
	s_nop 1
	v_cndmask_b32_e32 v80, v204, v205, vcc
	v_mov_b32_e32 v81, v80
	v_mov_b32_e32 v82, v80
	v_mov_b32_e32 v83, v80
	v_mov_b32_e32 v84, v80
	v_mov_b32_e32 v85, v80
	v_mov_b32_e32 v86, v80
	v_mov_b32_e32 v87, v80
	v_mov_b32_e32 v88, v80
	v_mov_b32_e32 v89, v80
	v_mov_b32_e32 v90, v80
	v_mov_b32_e32 v91, v80
	v_mov_b32_e32 v92, v80
	v_mov_b32_e32 v93, v80
	v_mov_b32_e32 v94, v80
	v_mov_b32_e32 v95, v80
	s_nop 0
	.p2align 6

.LBB0_1248:
	v_add_co_u32_e32 v210, vcc, 0xfffa0000, v210
	s_nop 1
	v_addc_co_u32_e32 v211, vcc, -1, v211, vcc
	v_add_co_u32_e32 v208, vcc, 0xffffff80, v208
	s_nop 1
	v_addc_co_u32_e32 v209, vcc, -1, v209, vcc
	v_mbcnt_lo_u32_b32 v249, -1, 0
	v_mbcnt_hi_u32_b32 v249, -1, v249
	v_and_b32_e32 v250, 15, v249
	v_bfe_u32 v249, v249, 4, 1
	v_cmp_eq_u32_e32 vcc, v249, v250
	v_mov_b32_e32 v249, s68
	s_nop 1
	v_cndmask_b32_e32 v244, 0, v249, vcc
	v_cndmask_b32_e32 v245, 0, v249, vcc
	v_cndmask_b32_e32 v246, 0, v249, vcc
	v_cndmask_b32_e32 v247, 0, v249, vcc
	v_add_u32_e32 v248, s21, v217
	ds_read_b128 v[226:229], v248 offset:17408
	ds_read_b128 v[230:233], v248 offset:22016
	ds_read_b128 v[236:239], v248 offset:17440
	ds_read_b128 v[240:243], v248 offset:22048
	s_add_i32 s4, s21, 0x8c00
	s_cmp_lg_u32 s21, 0x11800
	s_cselect_b32 s4, s4, 0
	v_exp_f32_e32 v64, v64
	v_exp_f32_e32 v65, v65
	v_exp_f32_e32 v66, v66
	v_exp_f32_e32 v67, v67
	v_exp_f32_e32 v68, v68
	v_exp_f32_e32 v69, v69
	v_exp_f32_e32 v70, v70
	v_exp_f32_e32 v71, v71
	v_cvt_pk_bf16_f32 v64, v64, v65
	v_cvt_pk_bf16_f32 v65, v66, v67
	v_cvt_pk_bf16_f32 v66, v68, v69
	v_cvt_pk_bf16_f32 v67, v70, v71
	s_nop 1
	.p2align 6
